# v9: + conditioning-vector loads of the adaLN silu staged up front (34 loads in flight) + lambda dot product loads in flight
# baseline (speedup 1.0000x reference)
; DI void phase_mods(float* mods, char* smem, int wv_) {
;     ...
;   for (int w = blockIdx.x; w < 192; w += gridDim.x) {
;     const int l = w / 96, n0 = (w % 96) * 64;
;     __syncthreads();
;     for (int idx = tid; idx < 17 * 1024; idx += NTHR) {
;       const int b = idx >> 10, k = idx & 1023;
;       const float v = (b < 16) ? p->c[b * 1024 + k] : p->c_ctx[k];
;       sil[idx] = v / (1.f + expf(-v));
;     }
;     __syncthreads();
.LBB0_22:
	s_barrier
	s_and_saveexec_b64 s[14:15], s[2:3]
	s_cbranch_execz .LBB0_29
	s_mov_b64 s[16:17], 0
	v_mov_b32_e32 v14, v1
	v_mov_b64_e32 v[10:11], v[6:7]
	v_mov_b32_e32 v15, v0
	s_load_dwordx2 s[30:31], s[8:9], 0x8
	s_load_dwordx2 s[34:35], s[8:9], 0x18
	s_waitcnt lgkmcnt(0)
	global_load_dword v40, v1, s[30:31]
	global_load_dword v41, v1, s[30:31] offset:2048
	v_add_u32_e32 v36, 0x1000, v1
	global_load_dword v42, v36, s[30:31]
	global_load_dword v43, v36, s[30:31] offset:2048
	v_add_u32_e32 v36, 0x2000, v1
	global_load_dword v44, v36, s[30:31]
	global_load_dword v45, v36, s[30:31] offset:2048
	v_add_u32_e32 v36, 0x3000, v1
	global_load_dword v46, v36, s[30:31]
	global_load_dword v47, v36, s[30:31] offset:2048
	v_add_u32_e32 v36, 0x4000, v1
	global_load_dword v48, v36, s[30:31]
	global_load_dword v49, v36, s[30:31] offset:2048
	v_add_u32_e32 v36, 0x5000, v1
	global_load_dword v50, v36, s[30:31]
	global_load_dword v51, v36, s[30:31] offset:2048
	v_add_u32_e32 v36, 0x6000, v1
	global_load_dword v52, v36, s[30:31]
	global_load_dword v53, v36, s[30:31] offset:2048
	v_add_u32_e32 v36, 0x7000, v1
	global_load_dword v54, v36, s[30:31]
	global_load_dword v55, v36, s[30:31] offset:2048
	v_add_u32_e32 v36, 0x8000, v1
	global_load_dword v56, v36, s[30:31]
	global_load_dword v57, v36, s[30:31] offset:2048
	v_add_u32_e32 v36, 0x9000, v1
	global_load_dword v58, v36, s[30:31]
	global_load_dword v59, v36, s[30:31] offset:2048
	v_add_u32_e32 v36, 0xa000, v1
	global_load_dword v60, v36, s[30:31]
	global_load_dword v61, v36, s[30:31] offset:2048
	v_add_u32_e32 v36, 0xb000, v1
	global_load_dword v62, v36, s[30:31]
	global_load_dword v63, v36, s[30:31] offset:2048
	v_add_u32_e32 v36, 0xc000, v1
	global_load_dword v64, v36, s[30:31]
	global_load_dword v65, v36, s[30:31] offset:2048
	v_add_u32_e32 v36, 0xd000, v1
	global_load_dword v66, v36, s[30:31]
	global_load_dword v67, v36, s[30:31] offset:2048
	v_add_u32_e32 v36, 0xe000, v1
	global_load_dword v68, v36, s[30:31]
	global_load_dword v69, v36, s[30:31] offset:2048
	v_add_u32_e32 v36, 0xf000, v1
	global_load_dword v70, v36, s[30:31]
	global_load_dword v71, v36, s[30:31] offset:2048
	global_load_dword v72, v1, s[34:35]
	global_load_dword v73, v1, s[34:35] offset:2048
	s_waitcnt vmcnt(0)
	ds_write_b32 v1, v40 offset:0
	ds_write_b32 v1, v41 offset:2048
	ds_write_b32 v1, v42 offset:4096
	ds_write_b32 v1, v43 offset:6144
	ds_write_b32 v1, v44 offset:8192
	ds_write_b32 v1, v45 offset:10240
	ds_write_b32 v1, v46 offset:12288
	ds_write_b32 v1, v47 offset:14336
	ds_write_b32 v1, v48 offset:16384
	ds_write_b32 v1, v49 offset:18432
	ds_write_b32 v1, v50 offset:20480
	ds_write_b32 v1, v51 offset:22528
	ds_write_b32 v1, v52 offset:24576
	ds_write_b32 v1, v53 offset:26624
	ds_write_b32 v1, v54 offset:28672
	ds_write_b32 v1, v55 offset:30720
	ds_write_b32 v1, v56 offset:32768
	ds_write_b32 v1, v57 offset:34816
	ds_write_b32 v1, v58 offset:36864
	ds_write_b32 v1, v59 offset:38912
	ds_write_b32 v1, v60 offset:40960
	ds_write_b32 v1, v61 offset:43008
	ds_write_b32 v1, v62 offset:45056
	ds_write_b32 v1, v63 offset:47104
	ds_write_b32 v1, v64 offset:49152
	ds_write_b32 v1, v65 offset:51200
	ds_write_b32 v1, v66 offset:53248
	ds_write_b32 v1, v67 offset:55296
	ds_write_b32 v1, v68 offset:57344
	ds_write_b32 v1, v69 offset:59392
	ds_write_b32 v1, v70 offset:61440
	ds_write_b32 v1, v71 offset:63488
	v_add_u32_e32 v36, 0x10000, v1
	ds_write_b32 v36, v72
	ds_write_b32 v36, v73 offset:2048
	s_waitcnt lgkmcnt(0)
	s_branch .LBB0_25
.LBB0_24:
	s_or_b64 exec, exec, s[6:7]
	ds_read_b32 v2, v14
	v_cmp_lt_i32_e32 vcc, s23, v15
	s_or_b64 s[16:17], vcc, s[16:17]
	v_lshl_add_u64 v[10:11], v[10:11], 0, s[10:11]
	s_waitcnt lgkmcnt(0)
	v_mul_f32_e32 v12, 0xbfb8aa3b, v2
	v_rndne_f32_e32 v13, v12
	v_fma_f32 v16, v2, s20, -v12
	v_sub_f32_e32 v12, v12, v13
	v_fmac_f32_e32 v16, 0xb2a5705f, v2
	v_add_f32_e32 v12, v12, v16
	v_cvt_i32_f32_e32 v13, v13
	v_exp_f32_e32 v12, v12
	v_cmp_nlt_f32_e64 s[6:7], s21, v2
	v_add_u32_e32 v16, 0x200, v15
	v_ldexp_f32 v12, v12, v13
	v_cndmask_b32_e64 v12, 0, v12, s[6:7]
	v_cmp_ngt_f32_e64 s[6:7], s22, v2
	s_nop 1
	v_cndmask_b32_e64 v12, v31, v12, s[6:7]
	v_add_f32_e32 v12, 1.0, v12
	v_div_scale_f32 v13, s[6:7], v12, v12, v2
	v_rcp_f32_e32 v15, v13
	v_div_scale_f32 v17, vcc, v2, v12, v2
	v_fma_f32 v18, -v13, v15, 1.0
	v_fmac_f32_e32 v15, v18, v15
	v_mul_f32_e32 v18, v17, v15
	v_fma_f32 v19, -v13, v18, v17
	v_fmac_f32_e32 v18, v19, v15
	v_fma_f32 v13, -v13, v18, v17
	v_div_fmas_f32 v13, v13, v15, v18
	v_div_fixup_f32 v2, v13, v12, v2
	ds_write_b32 v14, v2
	v_add_u32_e32 v14, 0x800, v14
	v_mov_b32_e32 v15, v16
	s_andn2_b64 exec, exec, s[16:17]
	s_cbranch_execz .LBB0_29
.LBB0_25:
	v_cmp_lt_i32_e32 vcc, s19, v15
	s_and_saveexec_b64 s[6:7], vcc
	s_xor_b64 s[6:7], exec, s[6:7]
	s_cbranch_execz .LBB0_27
	v_and_b32_e32 v2, 0x3ff, v15
	v_lshlrev_b32_e32 v2, 2, v2
.LBB0_27:
	s_andn2_saveexec_b64 s[6:7], s[6:7]
	s_cbranch_execz .LBB0_24
	s_branch .LBB0_24
